# v43: prep weight-conversion jobs - the 16 folded-gain loads of the 8 tile slots issued behind the tile loads instead of one serialized load-wait per slot
# speedup vs baseline: 1.0165x; 1.0165x over previous
.LBB0_55:
	s_or_b64 exec, exec, s[6:7]
	v_mov_b32_e32 v220, v68
	v_ashrrev_i32_e32 v221, 31, v68
	v_lshl_add_u64 v[220:221], v[220:221], 2, s[70:71]
	global_load_dword v224, v[220:221], off
	global_load_dword v225, v[220:221], off offset:128
	v_mov_b32_e32 v222, v70
	v_ashrrev_i32_e32 v223, 31, v70
	v_lshl_add_u64 v[222:223], v[222:223], 2, s[70:71]
	global_load_dword v226, v[222:223], off
	global_load_dword v227, v[222:223], off offset:128
	v_mov_b32_e32 v220, v72
	v_ashrrev_i32_e32 v221, 31, v72
	v_lshl_add_u64 v[220:221], v[220:221], 2, s[70:71]
	global_load_dword v228, v[220:221], off
	global_load_dword v229, v[220:221], off offset:128
	v_mov_b32_e32 v222, v74
	v_ashrrev_i32_e32 v223, 31, v74
	v_lshl_add_u64 v[222:223], v[222:223], 2, s[70:71]
	global_load_dword v230, v[222:223], off
	global_load_dword v231, v[222:223], off offset:128
	v_mov_b32_e32 v220, v76
	v_ashrrev_i32_e32 v221, 31, v76
	v_lshl_add_u64 v[220:221], v[220:221], 2, s[70:71]
	global_load_dword v232, v[220:221], off
	global_load_dword v233, v[220:221], off offset:128
	v_mov_b32_e32 v222, v78
	v_ashrrev_i32_e32 v223, 31, v78
	v_lshl_add_u64 v[222:223], v[222:223], 2, s[70:71]
	global_load_dword v234, v[222:223], off
	global_load_dword v235, v[222:223], off offset:128
	v_mov_b32_e32 v220, v80
	v_ashrrev_i32_e32 v221, 31, v80
	v_lshl_add_u64 v[220:221], v[220:221], 2, s[70:71]
	global_load_dword v236, v[220:221], off
	global_load_dword v237, v[220:221], off offset:128
	v_mov_b32_e32 v222, v82
	v_ashrrev_i32_e32 v223, 31, v82
	v_lshl_add_u64 v[222:223], v[222:223], 2, s[70:71]
	global_load_dword v238, v[222:223], off
	global_load_dword v239, v[222:223], off offset:128
	s_mov_b64 s[4:5], -1
	s_and_b64 vcc, exec, s[64:65]
	v_add_u32_e32 v77, v89, v90
	s_cbranch_vccz .LBB0_57
	s_waitcnt vmcnt(0)
	ds_write2_b32 v77, v12, v13 offset1:1
	ds_write2_b32 v77, v14, v15 offset0:2 offset1:3
	s_mov_b64 s[4:5], 0
.LBB0_57:
	s_andn2_b64 vcc, exec, s[4:5]
	v_mov_b32_e32 v64, 1.0
	s_cbranch_vccnz .LBB0_59
	v_ashrrev_i32_e32 v69, 31, v68
	v_lshl_add_u64 v[68:69], v[68:69], 2, s[70:71]
	s_waitcnt vmcnt(0)
	v_mov_b32_e32 v84, v224
	v_mov_b32_e32 v64, v225
	v_pk_mul_f32 v[12:13], v[12:13], v[84:85] op_sel_hi:[1,0]
	v_pk_mul_f32 v[14:15], v[14:15], v[84:85] op_sel_hi:[1,0]
	ds_write2_b32 v77, v12, v13 offset1:1
	ds_write2_b32 v77, v14, v15 offset0:2 offset1:3

.LBB0_61:
	s_andn2_b64 vcc, exec, s[4:5]
	v_mov_b32_e32 v0, 1.0
	s_cbranch_vccnz .LBB0_63
	v_ashrrev_i32_e32 v71, 31, v70
	v_lshl_add_u64 v[12:13], v[70:71], 2, s[70:71]
	s_waitcnt vmcnt(0)
	v_mov_b32_e32 v14, v226
	v_mov_b32_e32 v0, v227
	v_pk_mul_f32 v[12:13], v[16:17], v[14:15] op_sel_hi:[1,0]
	v_pk_mul_f32 v[14:15], v[18:19], v[14:15] op_sel_hi:[1,0]
	ds_write2_b32 v1, v12, v13 offset1:1
	ds_write2_b32 v2, v14, v15 offset1:1

.LBB0_65:
	s_andn2_b64 vcc, exec, s[4:5]
	v_mov_b32_e32 v0, 1.0
	s_cbranch_vccnz .LBB0_67
	v_ashrrev_i32_e32 v73, 31, v72
	v_lshl_add_u64 v[4:5], v[72:73], 2, s[70:71]
	s_waitcnt vmcnt(0)
	v_mov_b32_e32 v6, v228
	v_mov_b32_e32 v0, v229
	v_pk_mul_f32 v[4:5], v[24:25], v[6:7] op_sel_hi:[1,0]
	v_pk_mul_f32 v[6:7], v[26:27], v[6:7] op_sel_hi:[1,0]
	ds_write2_b32 v1, v4, v5 offset1:1
	ds_write2_b32 v2, v6, v7 offset1:1

.LBB0_69:
	s_andn2_b64 vcc, exec, s[4:5]
	v_mov_b32_e32 v0, 1.0
	s_cbranch_vccnz .LBB0_71
	v_ashrrev_i32_e32 v75, 31, v74
	v_lshl_add_u64 v[4:5], v[74:75], 2, s[70:71]
	s_waitcnt vmcnt(0)
	v_mov_b32_e32 v6, v230
	v_mov_b32_e32 v0, v231
	v_pk_mul_f32 v[4:5], v[32:33], v[6:7] op_sel_hi:[1,0]
	v_pk_mul_f32 v[6:7], v[34:35], v[6:7] op_sel_hi:[1,0]
	ds_write2_b32 v1, v4, v5 offset1:1
	ds_write2_b32 v2, v6, v7 offset1:1

.LBB0_73:
	s_andn2_b64 vcc, exec, s[4:5]
	v_mov_b32_e32 v0, 1.0
	s_cbranch_vccnz .LBB0_75
	v_ashrrev_i32_e32 v77, 31, v76
	v_lshl_add_u64 v[0:1], v[76:77], 2, s[70:71]
	s_waitcnt vmcnt(0)
	s_nop 0
	v_mov_b32_e32 v2, v232
	v_mov_b32_e32 v0, v233
	v_pk_mul_f32 v[4:5], v[40:41], v[2:3] op_sel_hi:[1,0]
	v_pk_mul_f32 v[2:3], v[42:43], v[2:3] op_sel_hi:[1,0]
	ds_write2_b32 v91, v4, v5 offset1:1
	ds_write2_b32 v91, v2, v3 offset0:2 offset1:3

.LBB0_77:
	s_andn2_b64 vcc, exec, s[4:5]
	v_mov_b32_e32 v0, 1.0
	s_cbranch_vccnz .LBB0_79
	v_ashrrev_i32_e32 v79, 31, v78
	v_lshl_add_u64 v[0:1], v[78:79], 2, s[70:71]
	s_waitcnt vmcnt(0)
	s_nop 0
	v_mov_b32_e32 v2, v234
	v_mov_b32_e32 v0, v235
	v_pk_mul_f32 v[4:5], v[48:49], v[2:3] op_sel_hi:[1,0]
	v_pk_mul_f32 v[2:3], v[50:51], v[2:3] op_sel_hi:[1,0]
	ds_write2_b32 v92, v4, v5 offset1:1
	ds_write2_b32 v92, v2, v3 offset0:2 offset1:3

.LBB0_81:
	s_andn2_b64 vcc, exec, s[4:5]
	v_mov_b32_e32 v0, 1.0
	s_cbranch_vccnz .LBB0_83
	v_ashrrev_i32_e32 v81, 31, v80
	v_lshl_add_u64 v[0:1], v[80:81], 2, s[70:71]
	s_waitcnt vmcnt(0)
	s_nop 0
	v_mov_b32_e32 v2, v236
	v_mov_b32_e32 v0, v237
	v_pk_mul_f32 v[4:5], v[56:57], v[2:3] op_sel_hi:[1,0]
	v_pk_mul_f32 v[2:3], v[58:59], v[2:3] op_sel_hi:[1,0]
	ds_write2_b32 v93, v4, v5 offset1:1
	ds_write2_b32 v93, v2, v3 offset0:2 offset1:3

.LBB0_85:
	s_andn2_b64 vcc, exec, s[6:7]
	v_mov_b32_e32 v0, 1.0
	s_cbranch_vccnz .LBB0_87
	v_ashrrev_i32_e32 v83, 31, v82
	v_lshl_add_u64 v[0:1], v[82:83], 2, s[70:71]
	s_waitcnt vmcnt(0)
	s_nop 0
	v_mov_b32_e32 v2, v238
	v_mov_b32_e32 v0, v239
	v_pk_mul_f32 v[4:5], v[60:61], v[2:3] op_sel_hi:[1,0]
	v_pk_mul_f32 v[2:3], v[62:63], v[2:3] op_sel_hi:[1,0]
	ds_write2_b32 v94, v4, v5 offset1:1
	ds_write2_b32 v94, v2, v3 offset0:2 offset1:3

.LBB0_267:
	s_or_b64 exec, exec, s[6:7]
	v_mov_b32_e32 v220, v68
	v_ashrrev_i32_e32 v221, 31, v68
	v_lshl_add_u64 v[220:221], v[220:221], 2, s[0:1]
	global_load_dword v224, v[220:221], off
	global_load_dword v225, v[220:221], off offset:128
	v_mov_b32_e32 v222, v70
	v_ashrrev_i32_e32 v223, 31, v70
	v_lshl_add_u64 v[222:223], v[222:223], 2, s[0:1]
	global_load_dword v226, v[222:223], off
	global_load_dword v227, v[222:223], off offset:128
	v_mov_b32_e32 v220, v72
	v_ashrrev_i32_e32 v221, 31, v72
	v_lshl_add_u64 v[220:221], v[220:221], 2, s[0:1]
	global_load_dword v228, v[220:221], off
	global_load_dword v229, v[220:221], off offset:128
	v_mov_b32_e32 v222, v74
	v_ashrrev_i32_e32 v223, 31, v74
	v_lshl_add_u64 v[222:223], v[222:223], 2, s[0:1]
	global_load_dword v230, v[222:223], off
	global_load_dword v231, v[222:223], off offset:128
	v_mov_b32_e32 v220, v76
	v_ashrrev_i32_e32 v221, 31, v76
	v_lshl_add_u64 v[220:221], v[220:221], 2, s[0:1]
	global_load_dword v232, v[220:221], off
	global_load_dword v233, v[220:221], off offset:128
	v_mov_b32_e32 v222, v78
	v_ashrrev_i32_e32 v223, 31, v78
	v_lshl_add_u64 v[222:223], v[222:223], 2, s[0:1]
	global_load_dword v234, v[222:223], off
	global_load_dword v235, v[222:223], off offset:128
	v_mov_b32_e32 v220, v80
	v_ashrrev_i32_e32 v221, 31, v80
	v_lshl_add_u64 v[220:221], v[220:221], 2, s[0:1]
	global_load_dword v236, v[220:221], off
	global_load_dword v237, v[220:221], off offset:128
	v_mov_b32_e32 v222, v82
	v_ashrrev_i32_e32 v223, 31, v82
	v_lshl_add_u64 v[222:223], v[222:223], 2, s[0:1]
	global_load_dword v238, v[222:223], off
	global_load_dword v239, v[222:223], off offset:128
	s_mov_b64 s[4:5], -1
	s_and_b64 vcc, exec, s[64:65]
	v_add_u32_e32 v84, v89, v90
	s_cbranch_vccz .LBB0_269
	s_waitcnt vmcnt(0)
	ds_write2_b32 v84, v4, v5 offset1:1
	ds_write2_b32 v84, v6, v7 offset0:2 offset1:3
	s_mov_b64 s[4:5], 0
.LBB0_269:
	s_andn2_b64 vcc, exec, s[4:5]
	v_mov_b32_e32 v64, 1.0
	s_cbranch_vccnz .LBB0_271
	v_lshl_add_u64 v[68:69], v[68:69], 2, s[0:1]
	s_waitcnt vmcnt(0)
	v_mov_b32_e32 v96, v224
	v_mov_b32_e32 v64, v225
	v_pk_mul_f32 v[4:5], v[4:5], v[96:97] op_sel_hi:[1,0]
	v_pk_mul_f32 v[6:7], v[6:7], v[96:97] op_sel_hi:[1,0]
	ds_write2_b32 v84, v4, v5 offset1:1
	ds_write2_b32 v84, v6, v7 offset0:2 offset1:3

.LBB0_273:
	s_andn2_b64 vcc, exec, s[4:5]
	v_mov_b32_e32 v0, 1.0
	s_cbranch_vccnz .LBB0_275
	v_lshl_add_u64 v[4:5], v[70:71], 2, s[0:1]
	s_waitcnt vmcnt(0)
	v_mov_b32_e32 v6, v226
	v_mov_b32_e32 v0, v227
	v_pk_mul_f32 v[4:5], v[12:13], v[6:7] op_sel_hi:[1,0]
	v_pk_mul_f32 v[6:7], v[14:15], v[6:7] op_sel_hi:[1,0]
	ds_write2_b32 v1, v4, v5 offset1:1
	ds_write2_b32 v2, v6, v7 offset1:1

.LBB0_277:
	s_andn2_b64 vcc, exec, s[4:5]
	v_mov_b32_e32 v0, 1.0
	s_cbranch_vccnz .LBB0_279
	v_lshl_add_u64 v[4:5], v[72:73], 2, s[0:1]
	s_waitcnt vmcnt(0)
	v_mov_b32_e32 v6, v228
	v_mov_b32_e32 v0, v229
	v_pk_mul_f32 v[4:5], v[20:21], v[6:7] op_sel_hi:[1,0]
	v_pk_mul_f32 v[6:7], v[22:23], v[6:7] op_sel_hi:[1,0]
	ds_write2_b32 v1, v4, v5 offset1:1
	ds_write2_b32 v2, v6, v7 offset1:1

.LBB0_281:
	s_andn2_b64 vcc, exec, s[4:5]
	v_mov_b32_e32 v0, 1.0
	s_cbranch_vccnz .LBB0_283
	v_lshl_add_u64 v[4:5], v[74:75], 2, s[0:1]
	s_waitcnt vmcnt(0)
	v_mov_b32_e32 v6, v230
	v_mov_b32_e32 v0, v231
	v_pk_mul_f32 v[4:5], v[28:29], v[6:7] op_sel_hi:[1,0]
	v_pk_mul_f32 v[6:7], v[30:31], v[6:7] op_sel_hi:[1,0]
	ds_write2_b32 v1, v4, v5 offset1:1
	ds_write2_b32 v2, v6, v7 offset1:1

.LBB0_285:
	s_andn2_b64 vcc, exec, s[4:5]
	v_mov_b32_e32 v0, 1.0
	s_cbranch_vccnz .LBB0_287
	v_lshl_add_u64 v[0:1], v[76:77], 2, s[0:1]
	s_waitcnt vmcnt(0)
	s_nop 0
	v_mov_b32_e32 v2, v232
	v_mov_b32_e32 v0, v233
	v_pk_mul_f32 v[4:5], v[36:37], v[2:3] op_sel_hi:[1,0]
	v_pk_mul_f32 v[2:3], v[38:39], v[2:3] op_sel_hi:[1,0]
	ds_write2_b32 v91, v4, v5 offset1:1
	ds_write2_b32 v91, v2, v3 offset0:2 offset1:3

.LBB0_289:
	s_andn2_b64 vcc, exec, s[6:7]
	v_mov_b32_e32 v0, 1.0
	s_cbranch_vccnz .LBB0_291
	v_lshl_add_u64 v[0:1], v[78:79], 2, s[0:1]
	s_waitcnt vmcnt(0)
	s_nop 0
	v_mov_b32_e32 v2, v234
	v_mov_b32_e32 v0, v235
	v_pk_mul_f32 v[4:5], v[44:45], v[2:3] op_sel_hi:[1,0]
	v_pk_mul_f32 v[2:3], v[46:47], v[2:3] op_sel_hi:[1,0]
	ds_write2_b32 v92, v4, v5 offset1:1
	ds_write2_b32 v92, v2, v3 offset0:2 offset1:3

.LBB0_293:
	s_andn2_b64 vcc, exec, s[10:11]
	v_mov_b32_e32 v0, 1.0
	s_cbranch_vccnz .LBB0_295
	v_lshl_add_u64 v[0:1], v[80:81], 2, s[0:1]
	s_waitcnt vmcnt(0)
	s_nop 0
	v_mov_b32_e32 v2, v236
	v_mov_b32_e32 v0, v237
	v_pk_mul_f32 v[4:5], v[52:53], v[2:3] op_sel_hi:[1,0]
	v_pk_mul_f32 v[2:3], v[54:55], v[2:3] op_sel_hi:[1,0]
	ds_write2_b32 v93, v4, v5 offset1:1
	ds_write2_b32 v93, v2, v3 offset0:2 offset1:3

.LBB0_297:
	s_andn2_b64 vcc, exec, s[12:13]
	v_mov_b32_e32 v0, 1.0
	s_cbranch_vccnz .LBB0_299
	v_lshl_add_u64 v[0:1], v[82:83], 2, s[0:1]
	s_waitcnt vmcnt(0)
	s_nop 0
	v_mov_b32_e32 v2, v238
	v_mov_b32_e32 v0, v239
	v_pk_mul_f32 v[4:5], v[60:61], v[2:3] op_sel_hi:[1,0]
	v_pk_mul_f32 v[2:3], v[62:63], v[2:3] op_sel_hi:[1,0]
	ds_write2_b32 v94, v4, v5 offset1:1
	ds_write2_b32 v94, v2, v3 offset0:2 offset1:3

.LBB0_355:
	s_or_b64 exec, exec, s[6:7]
	v_mov_b32_e32 v220, v68
	v_ashrrev_i32_e32 v221, 31, v68
	v_lshl_add_u64 v[220:221], v[220:221], 2, s[0:1]
	global_load_dword v224, v[220:221], off
	global_load_dword v225, v[220:221], off offset:128
	v_mov_b32_e32 v222, v70
	v_ashrrev_i32_e32 v223, 31, v70
	v_lshl_add_u64 v[222:223], v[222:223], 2, s[0:1]
	global_load_dword v226, v[222:223], off
	global_load_dword v227, v[222:223], off offset:128
	v_mov_b32_e32 v220, v72
	v_ashrrev_i32_e32 v221, 31, v72
	v_lshl_add_u64 v[220:221], v[220:221], 2, s[0:1]
	global_load_dword v228, v[220:221], off
	global_load_dword v229, v[220:221], off offset:128
	v_mov_b32_e32 v222, v74
	v_ashrrev_i32_e32 v223, 31, v74
	v_lshl_add_u64 v[222:223], v[222:223], 2, s[0:1]
	global_load_dword v230, v[222:223], off
	global_load_dword v231, v[222:223], off offset:128
	v_mov_b32_e32 v220, v76
	v_ashrrev_i32_e32 v221, 31, v76
	v_lshl_add_u64 v[220:221], v[220:221], 2, s[0:1]
	global_load_dword v232, v[220:221], off
	global_load_dword v233, v[220:221], off offset:128
	v_mov_b32_e32 v222, v78
	v_ashrrev_i32_e32 v223, 31, v78
	v_lshl_add_u64 v[222:223], v[222:223], 2, s[0:1]
	global_load_dword v234, v[222:223], off
	global_load_dword v235, v[222:223], off offset:128
	v_mov_b32_e32 v220, v80
	v_ashrrev_i32_e32 v221, 31, v80
	v_lshl_add_u64 v[220:221], v[220:221], 2, s[0:1]
	global_load_dword v236, v[220:221], off
	global_load_dword v237, v[220:221], off offset:128
	v_mov_b32_e32 v222, v82
	v_ashrrev_i32_e32 v223, 31, v82
	v_lshl_add_u64 v[222:223], v[222:223], 2, s[0:1]
	global_load_dword v238, v[222:223], off
	global_load_dword v239, v[222:223], off offset:128
	s_mov_b64 s[4:5], -1
	s_and_b64 vcc, exec, s[64:65]
	v_add_u32_e32 v77, v89, v90
	s_cbranch_vccz .LBB0_357
	s_waitcnt vmcnt(0)
	ds_write2_b32 v77, v12, v13 offset1:1
	ds_write2_b32 v77, v14, v15 offset0:2 offset1:3
	s_mov_b64 s[4:5], 0
.LBB0_357:
	s_andn2_b64 vcc, exec, s[4:5]
	v_mov_b32_e32 v64, 1.0
	s_cbranch_vccnz .LBB0_359
	v_ashrrev_i32_e32 v69, 31, v68
	v_lshl_add_u64 v[68:69], v[68:69], 2, s[0:1]
	s_waitcnt vmcnt(0)
	v_mov_b32_e32 v84, v224
	v_mov_b32_e32 v64, v225
	v_pk_mul_f32 v[12:13], v[12:13], v[84:85] op_sel_hi:[1,0]
	v_pk_mul_f32 v[14:15], v[14:15], v[84:85] op_sel_hi:[1,0]
	ds_write2_b32 v77, v12, v13 offset1:1
	ds_write2_b32 v77, v14, v15 offset0:2 offset1:3

.LBB0_361:
	s_andn2_b64 vcc, exec, s[4:5]
	v_mov_b32_e32 v0, 1.0
	s_cbranch_vccnz .LBB0_363
	v_ashrrev_i32_e32 v71, 31, v70
	v_lshl_add_u64 v[12:13], v[70:71], 2, s[0:1]
	s_waitcnt vmcnt(0)
	v_mov_b32_e32 v14, v226
	v_mov_b32_e32 v0, v227
	v_pk_mul_f32 v[12:13], v[16:17], v[14:15] op_sel_hi:[1,0]
	v_pk_mul_f32 v[14:15], v[18:19], v[14:15] op_sel_hi:[1,0]
	ds_write2_b32 v1, v12, v13 offset1:1
	ds_write2_b32 v2, v14, v15 offset1:1

.LBB0_365:
	s_andn2_b64 vcc, exec, s[4:5]
	v_mov_b32_e32 v0, 1.0
	s_cbranch_vccnz .LBB0_367
	v_ashrrev_i32_e32 v73, 31, v72
	v_lshl_add_u64 v[4:5], v[72:73], 2, s[0:1]
	s_waitcnt vmcnt(0)
	v_mov_b32_e32 v6, v228
	v_mov_b32_e32 v0, v229
	v_pk_mul_f32 v[4:5], v[24:25], v[6:7] op_sel_hi:[1,0]
	v_pk_mul_f32 v[6:7], v[26:27], v[6:7] op_sel_hi:[1,0]
	ds_write2_b32 v1, v4, v5 offset1:1
	ds_write2_b32 v2, v6, v7 offset1:1

.LBB0_369:
	s_andn2_b64 vcc, exec, s[4:5]
	v_mov_b32_e32 v0, 1.0
	s_cbranch_vccnz .LBB0_371
	v_ashrrev_i32_e32 v75, 31, v74
	v_lshl_add_u64 v[4:5], v[74:75], 2, s[0:1]
	s_waitcnt vmcnt(0)
	v_mov_b32_e32 v6, v230
	v_mov_b32_e32 v0, v231
	v_pk_mul_f32 v[4:5], v[32:33], v[6:7] op_sel_hi:[1,0]
	v_pk_mul_f32 v[6:7], v[34:35], v[6:7] op_sel_hi:[1,0]
	ds_write2_b32 v1, v4, v5 offset1:1
	ds_write2_b32 v2, v6, v7 offset1:1

.LBB0_373:
	s_andn2_b64 vcc, exec, s[4:5]
	v_mov_b32_e32 v0, 1.0
	s_cbranch_vccnz .LBB0_375
	v_ashrrev_i32_e32 v77, 31, v76
	v_lshl_add_u64 v[0:1], v[76:77], 2, s[0:1]
	s_waitcnt vmcnt(0)
	s_nop 0
	v_mov_b32_e32 v2, v232
	v_mov_b32_e32 v0, v233
	v_pk_mul_f32 v[4:5], v[40:41], v[2:3] op_sel_hi:[1,0]
	v_pk_mul_f32 v[2:3], v[42:43], v[2:3] op_sel_hi:[1,0]
	ds_write2_b32 v91, v4, v5 offset1:1
	ds_write2_b32 v91, v2, v3 offset0:2 offset1:3

.LBB0_377:
	s_andn2_b64 vcc, exec, s[4:5]
	v_mov_b32_e32 v0, 1.0
	s_cbranch_vccnz .LBB0_379
	v_ashrrev_i32_e32 v79, 31, v78
	v_lshl_add_u64 v[0:1], v[78:79], 2, s[0:1]
	s_waitcnt vmcnt(0)
	s_nop 0
	v_mov_b32_e32 v2, v234
	v_mov_b32_e32 v0, v235
	v_pk_mul_f32 v[4:5], v[48:49], v[2:3] op_sel_hi:[1,0]
	v_pk_mul_f32 v[2:3], v[50:51], v[2:3] op_sel_hi:[1,0]
	ds_write2_b32 v92, v4, v5 offset1:1
	ds_write2_b32 v92, v2, v3 offset0:2 offset1:3

.LBB0_381:
	s_andn2_b64 vcc, exec, s[6:7]
	v_mov_b32_e32 v0, 1.0
	s_cbranch_vccnz .LBB0_383
	v_ashrrev_i32_e32 v81, 31, v80
	v_lshl_add_u64 v[0:1], v[80:81], 2, s[0:1]
	s_waitcnt vmcnt(0)
	s_nop 0
	v_mov_b32_e32 v2, v236
	v_mov_b32_e32 v0, v237
	v_pk_mul_f32 v[4:5], v[56:57], v[2:3] op_sel_hi:[1,0]
	v_pk_mul_f32 v[2:3], v[58:59], v[2:3] op_sel_hi:[1,0]
	ds_write2_b32 v93, v4, v5 offset1:1
	ds_write2_b32 v93, v2, v3 offset0:2 offset1:3

.LBB0_385:
	s_andn2_b64 vcc, exec, s[10:11]
	v_mov_b32_e32 v0, 1.0
	s_cbranch_vccnz .LBB0_387
	v_ashrrev_i32_e32 v83, 31, v82
	v_lshl_add_u64 v[0:1], v[82:83], 2, s[0:1]
	s_waitcnt vmcnt(0)
	s_nop 0
	v_mov_b32_e32 v2, v238
	v_mov_b32_e32 v0, v239
	v_pk_mul_f32 v[4:5], v[60:61], v[2:3] op_sel_hi:[1,0]
	v_pk_mul_f32 v[2:3], v[62:63], v[2:3] op_sel_hi:[1,0]
	ds_write2_b32 v94, v4, v5 offset1:1
	ds_write2_b32 v94, v2, v3 offset0:2 offset1:3

.LBB0_436:
	s_or_b64 exec, exec, s[6:7]
	v_mov_b32_e32 v220, v68
	v_ashrrev_i32_e32 v221, 31, v68
	v_lshl_add_u64 v[220:221], v[220:221], 2, s[24:25]
	global_load_dword v224, v[220:221], off
	global_load_dword v225, v[220:221], off offset:128
	v_mov_b32_e32 v222, v70
	v_ashrrev_i32_e32 v223, 31, v70
	v_lshl_add_u64 v[222:223], v[222:223], 2, s[24:25]
	global_load_dword v226, v[222:223], off
	global_load_dword v227, v[222:223], off offset:128
	v_mov_b32_e32 v220, v72
	v_ashrrev_i32_e32 v221, 31, v72
	v_lshl_add_u64 v[220:221], v[220:221], 2, s[24:25]
	global_load_dword v228, v[220:221], off
	global_load_dword v229, v[220:221], off offset:128
	v_mov_b32_e32 v222, v74
	v_ashrrev_i32_e32 v223, 31, v74
	v_lshl_add_u64 v[222:223], v[222:223], 2, s[24:25]
	global_load_dword v230, v[222:223], off
	global_load_dword v231, v[222:223], off offset:128
	v_mov_b32_e32 v220, v76
	v_ashrrev_i32_e32 v221, 31, v76
	v_lshl_add_u64 v[220:221], v[220:221], 2, s[24:25]
	global_load_dword v232, v[220:221], off
	global_load_dword v233, v[220:221], off offset:128
	v_mov_b32_e32 v222, v78
	v_ashrrev_i32_e32 v223, 31, v78
	v_lshl_add_u64 v[222:223], v[222:223], 2, s[24:25]
	global_load_dword v234, v[222:223], off
	global_load_dword v235, v[222:223], off offset:128
	v_mov_b32_e32 v220, v80
	v_ashrrev_i32_e32 v221, 31, v80
	v_lshl_add_u64 v[220:221], v[220:221], 2, s[24:25]
	global_load_dword v236, v[220:221], off
	global_load_dword v237, v[220:221], off offset:128
	v_mov_b32_e32 v222, v82
	v_ashrrev_i32_e32 v223, 31, v82
	v_lshl_add_u64 v[222:223], v[222:223], 2, s[24:25]
	global_load_dword v238, v[222:223], off
	global_load_dword v239, v[222:223], off offset:128
	s_mov_b64 s[4:5], -1
	s_and_b64 vcc, exec, s[64:65]
	v_add_u32_e32 v77, v89, v90
	s_cbranch_vccz .LBB0_438
	s_waitcnt vmcnt(0)
	ds_write2_b32 v77, v12, v13 offset1:1
	ds_write2_b32 v77, v14, v15 offset0:2 offset1:3
	s_mov_b64 s[4:5], 0
.LBB0_438:
	s_andn2_b64 vcc, exec, s[4:5]
	v_mov_b32_e32 v64, 1.0
	s_cbranch_vccnz .LBB0_440
	v_ashrrev_i32_e32 v69, 31, v68
	v_lshl_add_u64 v[68:69], v[68:69], 2, s[24:25]
	s_waitcnt vmcnt(0)
	v_mov_b32_e32 v84, v224
	v_mov_b32_e32 v64, v225
	v_pk_mul_f32 v[12:13], v[12:13], v[84:85] op_sel_hi:[1,0]
	v_pk_mul_f32 v[14:15], v[14:15], v[84:85] op_sel_hi:[1,0]
	ds_write2_b32 v77, v12, v13 offset1:1
	ds_write2_b32 v77, v14, v15 offset0:2 offset1:3

.LBB0_442:
	s_andn2_b64 vcc, exec, s[4:5]
	v_mov_b32_e32 v0, 1.0
	s_cbranch_vccnz .LBB0_444
	v_ashrrev_i32_e32 v71, 31, v70
	v_lshl_add_u64 v[12:13], v[70:71], 2, s[24:25]
	s_waitcnt vmcnt(0)
	v_mov_b32_e32 v14, v226
	v_mov_b32_e32 v0, v227
	v_pk_mul_f32 v[12:13], v[16:17], v[14:15] op_sel_hi:[1,0]
	v_pk_mul_f32 v[14:15], v[18:19], v[14:15] op_sel_hi:[1,0]
	ds_write2_b32 v1, v12, v13 offset1:1
	ds_write2_b32 v2, v14, v15 offset1:1

.LBB0_446:
	s_andn2_b64 vcc, exec, s[4:5]
	v_mov_b32_e32 v0, 1.0
	s_cbranch_vccnz .LBB0_448
	v_ashrrev_i32_e32 v73, 31, v72
	v_lshl_add_u64 v[4:5], v[72:73], 2, s[24:25]
	s_waitcnt vmcnt(0)
	v_mov_b32_e32 v6, v228
	v_mov_b32_e32 v0, v229
	v_pk_mul_f32 v[4:5], v[24:25], v[6:7] op_sel_hi:[1,0]
	v_pk_mul_f32 v[6:7], v[26:27], v[6:7] op_sel_hi:[1,0]
	ds_write2_b32 v1, v4, v5 offset1:1
	ds_write2_b32 v2, v6, v7 offset1:1

.LBB0_450:
	s_andn2_b64 vcc, exec, s[4:5]
	v_mov_b32_e32 v0, 1.0
	s_cbranch_vccnz .LBB0_452
	v_ashrrev_i32_e32 v75, 31, v74
	v_lshl_add_u64 v[4:5], v[74:75], 2, s[24:25]
	s_waitcnt vmcnt(0)
	v_mov_b32_e32 v6, v230
	v_mov_b32_e32 v0, v231
	v_pk_mul_f32 v[4:5], v[32:33], v[6:7] op_sel_hi:[1,0]
	v_pk_mul_f32 v[6:7], v[34:35], v[6:7] op_sel_hi:[1,0]
	ds_write2_b32 v1, v4, v5 offset1:1
	ds_write2_b32 v2, v6, v7 offset1:1

.LBB0_454:
	s_andn2_b64 vcc, exec, s[4:5]
	v_mov_b32_e32 v0, 1.0
	s_cbranch_vccnz .LBB0_456
	v_ashrrev_i32_e32 v77, 31, v76
	v_lshl_add_u64 v[0:1], v[76:77], 2, s[24:25]
	s_waitcnt vmcnt(0)
	s_nop 0
	v_mov_b32_e32 v2, v232
	v_mov_b32_e32 v0, v233
	v_pk_mul_f32 v[4:5], v[40:41], v[2:3] op_sel_hi:[1,0]
	v_pk_mul_f32 v[2:3], v[42:43], v[2:3] op_sel_hi:[1,0]
	ds_write2_b32 v91, v4, v5 offset1:1
	ds_write2_b32 v91, v2, v3 offset0:2 offset1:3

.LBB0_458:
	s_andn2_b64 vcc, exec, s[4:5]
	v_mov_b32_e32 v0, 1.0
	s_cbranch_vccnz .LBB0_460
	v_ashrrev_i32_e32 v79, 31, v78
	v_lshl_add_u64 v[0:1], v[78:79], 2, s[24:25]
	s_waitcnt vmcnt(0)
	s_nop 0
	v_mov_b32_e32 v2, v234
	v_mov_b32_e32 v0, v235
	v_pk_mul_f32 v[4:5], v[48:49], v[2:3] op_sel_hi:[1,0]
	v_pk_mul_f32 v[2:3], v[50:51], v[2:3] op_sel_hi:[1,0]
	ds_write2_b32 v92, v4, v5 offset1:1
	ds_write2_b32 v92, v2, v3 offset0:2 offset1:3

.LBB0_462:
	s_andn2_b64 vcc, exec, s[6:7]
	v_mov_b32_e32 v0, 1.0
	s_cbranch_vccnz .LBB0_464
	v_ashrrev_i32_e32 v81, 31, v80
	v_lshl_add_u64 v[0:1], v[80:81], 2, s[24:25]
	s_waitcnt vmcnt(0)
	s_nop 0
	v_mov_b32_e32 v2, v236
	v_mov_b32_e32 v0, v237
	v_pk_mul_f32 v[4:5], v[56:57], v[2:3] op_sel_hi:[1,0]
	v_pk_mul_f32 v[2:3], v[58:59], v[2:3] op_sel_hi:[1,0]
	ds_write2_b32 v93, v4, v5 offset1:1
	ds_write2_b32 v93, v2, v3 offset0:2 offset1:3

.LBB0_466:
	s_andn2_b64 vcc, exec, s[10:11]
	v_mov_b32_e32 v0, 1.0
	s_cbranch_vccnz .LBB0_468
	v_ashrrev_i32_e32 v83, 31, v82
	v_lshl_add_u64 v[0:1], v[82:83], 2, s[24:25]
	s_waitcnt vmcnt(0)
	s_nop 0
	v_mov_b32_e32 v2, v238
	v_mov_b32_e32 v0, v239
	v_pk_mul_f32 v[4:5], v[60:61], v[2:3] op_sel_hi:[1,0]
	v_pk_mul_f32 v[2:3], v[62:63], v[2:3] op_sel_hi:[1,0]
	ds_write2_b32 v94, v4, v5 offset1:1
	ds_write2_b32 v94, v2, v3 offset0:2 offset1:3
